# diff-attention P.V block: bf16 converts placed before the V-fragment refill reads so two s_nop pads (and one spare s_nop) between MFMA groups go
# baseline (speedup 1.0000x reference)
; __device__ __forceinline__ unsigned cvtpk(float lo, float hi) { f32x2_t v = {lo, hi}; bf16x2_t b = __builtin_convertvector(v, bf16x2_t); return __builtin_bit_cast(unsigned, b); }
; #define ATT_MMAG(F, dvb) do { _Pragma("unroll") for (int j = 0; j < 4; ++j) o[dvb] = __builtin_amdgcn_mfma_f32_32x32x16_bf16(F[j], pb[j >> 1][j & 1], o[dvb], 0, 0, 0); } while (0)
; template <bool DIFF> ...
;     ...
;             const float d0 = c0 - m_run, d1 = c1 - m_run;
;             float rs0 = 0.f, rs1 = 0.f;
; #pragma unroll
;             for (int r = 0; r < 16; ++r) { s0[r] = __builtin_amdgcn_exp2f(__builtin_fmaf(s0[r], sc2, d0)); s1[r] = __builtin_amdgcn_exp2f(__builtin_fmaf(s1[r], sc2, d1)); rs0 += s0[r]; rs1 += s1[r]; }
;             l_run += rs0 + rs1;
;             bf16x8 pb[2][2];
; #pragma unroll
;             for (int g = 0; g < 2; ++g) {
;                 u32x4 w0, w1;
;                 w0.x = cvtpk(s0[8 * g], s0[8 * g + 1]); w0.y = cvtpk(s0[8 * g + 2], s0[8 * g + 3]); w0.z = cvtpk(s0[8 * g + 4], s0[8 * g + 5]); w0.w = cvtpk(s0[8 * g + 6], s0[8 * g + 7]);
;                 w1.x = cvtpk(s1[8 * g], s1[8 * g + 1]); w1.y = cvtpk(s1[8 * g + 2], s1[8 * g + 3]); w1.z = cvtpk(s1[8 * g + 4], s1[8 * g + 5]); w1.w = cvtpk(s1[8 * g + 6], s1[8 * g + 7]);
;                 pb[0][g] = __builtin_bit_cast(bf16x8, w0); pb[1][g] = __builtin_bit_cast(bf16x8, w1);
;             }
;             __builtin_amdgcn_sched_barrier(0);
;             ATT_MMAG(fa, 0); ATT_LOADG(fa, 2); __builtin_amdgcn_sched_barrier(0); ATT_MMAG(fb, 1); ATT_LOADG(fb, 3); __builtin_amdgcn_sched_barrier(0); ATT_MMAG(fa, 2); ATT_MMAG(fb, 3);
.LBB0_112:
	v_sub_f32_e32 v227, v213, v209
	v_sub_f32_e32 v226, v212, v209
	v_fmamk_f32 v98, v98, 0x3e38aa3b, v226
	v_fmamk_f32 v99, v99, 0x3e38aa3b, v226
	v_fmamk_f32 v100, v100, 0x3e38aa3b, v226
	v_fmamk_f32 v101, v101, 0x3e38aa3b, v226
	v_fmamk_f32 v102, v102, 0x3e38aa3b, v226
	v_fmamk_f32 v103, v103, 0x3e38aa3b, v226
	v_fmamk_f32 v104, v104, 0x3e38aa3b, v226
	v_fmamk_f32 v105, v105, 0x3e38aa3b, v226
	v_exp_f32_e32 v98, v98
	v_exp_f32_e32 v99, v99
	v_exp_f32_e32 v100, v100
	v_exp_f32_e32 v101, v101
	v_exp_f32_e32 v102, v102
	v_exp_f32_e32 v103, v103
	v_exp_f32_e32 v104, v104
	v_exp_f32_e32 v105, v105
	v_add_f32_e32 v212, v98, v100
	v_add_f32_e32 v213, v99, v101
	v_add_f32_e32 v212, v212, v102
	v_add_f32_e32 v213, v213, v103
	v_add_f32_e32 v212, v212, v104
	v_add_f32_e32 v213, v213, v105
	v_cvt_pk_bf16_f32 v98, v98, v99
	v_cvt_pk_bf16_f32 v99, v100, v101
	v_cvt_pk_bf16_f32 v100, v102, v103
	v_cvt_pk_bf16_f32 v101, v104, v105
	s_waitcnt lgkmcnt(8)
	s_nop 1
	v_mfma_f32_32x32x16_bf16 v[50:65], v[130:133], v[98:101], v[50:65]
	v_fmamk_f32 v106, v106, 0x3e38aa3b, v226
	v_fmamk_f32 v107, v107, 0x3e38aa3b, v226
	v_fmamk_f32 v108, v108, 0x3e38aa3b, v226
	v_fmamk_f32 v109, v109, 0x3e38aa3b, v226
	v_fmamk_f32 v110, v110, 0x3e38aa3b, v226
	v_fmamk_f32 v111, v111, 0x3e38aa3b, v226
	v_fmamk_f32 v112, v112, 0x3e38aa3b, v226
	v_mfma_f32_32x32x16_bf16 v[34:49], v[134:137], v[98:101], v[34:49]
	v_fmamk_f32 v113, v113, 0x3e38aa3b, v226
	v_exp_f32_e32 v106, v106
	v_exp_f32_e32 v107, v107
	v_exp_f32_e32 v108, v108
	v_exp_f32_e32 v109, v109
	v_exp_f32_e32 v110, v110
	v_exp_f32_e32 v111, v111
	v_mfma_f32_32x32x16_bf16 v[18:33], v[138:141], v[98:101], v[18:33]
	v_exp_f32_e32 v112, v112
	v_exp_f32_e32 v113, v113
	v_add_f32_e32 v212, v212, v106
	v_add_f32_e32 v213, v213, v107
	v_add_f32_e32 v212, v212, v108
	v_add_f32_e32 v213, v213, v109
	v_add_f32_e32 v212, v212, v110
	v_add_f32_e32 v213, v213, v111
	v_add_f32_e32 v212, v212, v112
	v_add_f32_e32 v213, v213, v113
	v_cvt_pk_bf16_f32 v106, v106, v107
	v_mfma_f32_32x32x16_bf16 v[2:17], v[142:145], v[98:101], v[2:17]
	v_cvt_pk_bf16_f32 v107, v108, v109
	v_cvt_pk_bf16_f32 v108, v110, v111
	v_cvt_pk_bf16_f32 v109, v112, v113
	ds_read_b64_tr_b16 v[130:131], v228 offset:24576
	ds_read_b64_tr_b16 v[132:133], v229 offset:26624
	ds_read_b64_tr_b16 v[134:135], v230 offset:24576
	ds_read_b64_tr_b16 v[136:137], v231 offset:26624
	ds_read_b64_tr_b16 v[138:139], v232 offset:24576
	ds_read_b64_tr_b16 v[140:141], v233 offset:26624
	ds_read_b64_tr_b16 v[142:143], v234 offset:24576
	ds_read_b64_tr_b16 v[144:145], v235 offset:26624
	s_waitcnt lgkmcnt(8)
	v_mfma_f32_32x32x16_bf16 v[50:65], v[146:149], v[106:109], v[50:65]
	v_fmamk_f32 v82, v82, 0x3e38aa3b, v227
	v_fmamk_f32 v83, v83, 0x3e38aa3b, v227
	v_fmamk_f32 v84, v84, 0x3e38aa3b, v227
	v_fmamk_f32 v85, v85, 0x3e38aa3b, v227
	v_fmamk_f32 v86, v86, 0x3e38aa3b, v227
	v_fmamk_f32 v87, v87, 0x3e38aa3b, v227
	v_fmamk_f32 v88, v88, 0x3e38aa3b, v227
	v_mfma_f32_32x32x16_bf16 v[34:49], v[150:153], v[106:109], v[34:49]
	v_fmamk_f32 v89, v89, 0x3e38aa3b, v227
	v_exp_f32_e32 v82, v82
	v_exp_f32_e32 v83, v83
	v_exp_f32_e32 v84, v84
	v_exp_f32_e32 v85, v85
	v_exp_f32_e32 v86, v86
	v_exp_f32_e32 v87, v87
	v_mfma_f32_32x32x16_bf16 v[18:33], v[154:157], v[106:109], v[18:33]
	v_exp_f32_e32 v88, v88
	v_exp_f32_e32 v89, v89
	v_add_f32_e32 v212, v212, v82
	v_add_f32_e32 v213, v213, v83
	v_add_f32_e32 v212, v212, v84
	v_add_f32_e32 v213, v213, v85
	v_add_f32_e32 v212, v212, v86
	v_add_f32_e32 v213, v213, v87
	v_add_f32_e32 v212, v212, v88
	v_add_f32_e32 v213, v213, v89
	v_cvt_pk_bf16_f32 v82, v82, v83
	v_mfma_f32_32x32x16_bf16 v[2:17], v[158:161], v[106:109], v[2:17]
	v_cvt_pk_bf16_f32 v83, v84, v85
	v_cvt_pk_bf16_f32 v84, v86, v87
	v_cvt_pk_bf16_f32 v85, v88, v89
	ds_read_b64_tr_b16 v[146:147], v228 offset:28672
	ds_read_b64_tr_b16 v[148:149], v229 offset:30720
	ds_read_b64_tr_b16 v[150:151], v230 offset:28672
	ds_read_b64_tr_b16 v[152:153], v231 offset:30720
	ds_read_b64_tr_b16 v[154:155], v232 offset:28672
	ds_read_b64_tr_b16 v[156:157], v233 offset:30720
	ds_read_b64_tr_b16 v[158:159], v234 offset:28672
	ds_read_b64_tr_b16 v[160:161], v235 offset:30720
	s_waitcnt lgkmcnt(8)
	v_mfma_f32_32x32x16_bf16 v[50:65], v[130:133], v[82:85], v[50:65]
	v_fmamk_f32 v90, v90, 0x3e38aa3b, v227
	v_fmamk_f32 v91, v91, 0x3e38aa3b, v227
	v_fmamk_f32 v92, v92, 0x3e38aa3b, v227
	v_fmamk_f32 v93, v93, 0x3e38aa3b, v227
	v_fmamk_f32 v94, v94, 0x3e38aa3b, v227
	v_fmamk_f32 v95, v95, 0x3e38aa3b, v227
	v_fmamk_f32 v96, v96, 0x3e38aa3b, v227
	v_mfma_f32_32x32x16_bf16 v[34:49], v[134:137], v[82:85], v[34:49]
	v_fmamk_f32 v97, v97, 0x3e38aa3b, v227
	v_exp_f32_e32 v90, v90
	v_exp_f32_e32 v91, v91
	v_exp_f32_e32 v92, v92
	v_exp_f32_e32 v93, v93
	v_exp_f32_e32 v94, v94
	v_exp_f32_e32 v95, v95
	v_mfma_f32_32x32x16_bf16 v[18:33], v[138:141], v[82:85], v[18:33]
	v_exp_f32_e32 v96, v96
	v_exp_f32_e32 v97, v97
	v_add_f32_e32 v212, v212, v90
	v_add_f32_e32 v213, v213, v91
	v_add_f32_e32 v212, v212, v92
	v_add_f32_e32 v213, v213, v93
	v_add_f32_e32 v212, v212, v94
	v_add_f32_e32 v213, v213, v95
	v_add_f32_e32 v212, v212, v96
	v_add_f32_e32 v213, v213, v97
	v_cvt_pk_bf16_f32 v90, v90, v91
	v_mfma_f32_32x32x16_bf16 v[2:17], v[142:145], v[82:85], v[2:17]
	v_cvt_pk_bf16_f32 v91, v92, v93
	v_cvt_pk_bf16_f32 v92, v94, v95
	v_cvt_pk_bf16_f32 v93, v96, v97
	s_waitcnt lgkmcnt(0)
	s_nop 1
	v_mfma_f32_32x32x16_bf16 v[50:65], v[146:149], v[90:93], v[50:65]
	v_mfma_f32_32x32x16_bf16 v[34:49], v[150:153], v[90:93], v[34:49]
	v_mfma_f32_32x32x16_bf16 v[18:33], v[154:157], v[90:93], v[18:33]
	v_mfma_f32_32x32x16_bf16 v[2:17], v[158:161], v[90:93], v[2:17]
	v_add_f32_e32 v212, v212, v213
	v_add_f32_e32 v205, v205, v212
